# hand-written pipelined rms-norm+modulate bodies for phases 6/9/13 (consecutive rows per wave, gain/shift/scale resident, next row prefetched)
# speedup vs baseline: 1.0112x; 1.0112x over previous
.LBB0_755:
	s_cmp_lt_i32 s78, 7
	s_cselect_b64 s[0:1], -1, 0
	s_cmp_gt_i32 s79, 6
	s_cselect_b64 s[2:3], -1, 0
	s_and_b64 s[0:1], s[0:1], s[2:3]
	s_andn2_b64 vcc, exec, s[0:1]
	s_cbranch_vccnz .LBB0_816
	s_cmp_lg_u32 s87, 0x100
	s_cbranch_scc1 .Lnr6_orig
	v_mbcnt_hi_u32_b32 v0, -1, v212
	v_and_b32_e32 v0, 63, v0
	v_lshlrev_b32_e32 v1, 5, v0
	v_lshlrev_b32_e32 v2, 4, v0
	v_mov_b32_e32 v9, 0x358637bd
	v_mov_b32_e32 v10, 0x260
	v_xor_b32_e32 v3, 1, v0
	v_lshlrev_b32_e32 v3, 2, v3
	v_xor_b32_e32 v4, 2, v0
	v_lshlrev_b32_e32 v4, 2, v4
	v_xor_b32_e32 v5, 4, v0
	v_lshlrev_b32_e32 v5, 2, v5
	v_xor_b32_e32 v6, 8, v0
	v_lshlrev_b32_e32 v6, 2, v6
	v_xor_b32_e32 v7, 16, v0
	v_lshlrev_b32_e32 v7, 2, v7
	v_xor_b32_e32 v8, 32, v0
	v_lshlrev_b32_e32 v8, 2, v8
	s_lshl_b32 s31, s96, 3
	s_add_u32 s31, s31, s93
	s_add_u32 s58, s76, 0xc989000
	s_addc_u32 s59, s77, 0
	s_add_u32 s62, s76, 0x11189000
	s_addc_u32 s63, s77, 0
	s_add_u32 s64, s76, 0x14000
	s_addc_u32 s65, s77, 0
	v_readlane_b32 s50, v244, 17
	v_readlane_b32 s51, v244, 18
	s_mov_b32 s23, -1
	s_mul_i32 s5, s31, 9
	s_lshr_b32 s5, s5, 1
	s_add_u32 s16, s31, 1
	s_mul_i32 s16, s16, 9
	s_lshr_b32 s16, s16, 1
	s_nop 0
	s_add_u32 s50, s50, 0x0
	s_addc_u32 s51, s51, 0
	s_add_u32 s54, s50, 0x1000
	s_addc_u32 s55, s51, 0
	s_cmp_ge_u32 s5, s16
	s_cbranch_scc1 .Lnr6_done
	global_load_dwordx4 v[20:23], v1, s[50:51] offset:0
	global_load_dwordx4 v[24:27], v1, s[50:51] offset:16
	global_load_dwordx4 v[28:31], v1, s[50:51] offset:2048
	global_load_dwordx4 v[32:35], v1, s[50:51] offset:2064
	global_load_dwordx4 v[36:39], v1, s[54:55] offset:0
	global_load_dwordx4 v[40:43], v1, s[54:55] offset:16
	global_load_dwordx4 v[44:47], v1, s[54:55] offset:2048
	global_load_dwordx4 v[48:51], v1, s[54:55] offset:2064
	s_lshl_b32 s35, s5, 13
	s_add_u32 s2, s58, s35
	s_addc_u32 s3, s59, 0
	s_add_u32 s6, s2, 0x1000
	s_addc_u32 s7, s3, 0
	global_load_dwordx4 v[116:119], v1, s[2:3] offset:0
	global_load_dwordx4 v[120:123], v1, s[2:3] offset:16
	global_load_dwordx4 v[124:127], v1, s[2:3] offset:2048
	global_load_dwordx4 v[128:131], v1, s[2:3] offset:2064
	global_load_dwordx4 v[132:135], v1, s[6:7] offset:0
	global_load_dwordx4 v[136:139], v1, s[6:7] offset:16
	global_load_dwordx4 v[140:143], v1, s[6:7] offset:2048
	global_load_dwordx4 v[144:147], v1, s[6:7] offset:2064
	s_waitcnt vmcnt(8)
.Lnr6_loop:
	s_add_u32 s31, s5, 1
	s_cmp_ge_u32 s31, s16
	s_cbranch_scc1 .Lnr6_last0
	s_lshl_b32 s35, s31, 13
	s_add_u32 s10, s58, s35
	s_addc_u32 s11, s59, 0
	s_add_u32 s32, s10, 0x1000
	s_addc_u32 s33, s11, 0
	global_load_dwordx4 v[148:151], v1, s[10:11] offset:0
	global_load_dwordx4 v[152:155], v1, s[10:11] offset:16
	global_load_dwordx4 v[156:159], v1, s[10:11] offset:2048
	global_load_dwordx4 v[160:163], v1, s[10:11] offset:2064
	global_load_dwordx4 v[164:167], v1, s[32:33] offset:0
	global_load_dwordx4 v[168:171], v1, s[32:33] offset:16
	global_load_dwordx4 v[172:175], v1, s[32:33] offset:2048
	global_load_dwordx4 v[176:179], v1, s[32:33] offset:2064
	s_cmp_ge_u32 s5, 0x900
	s_cselect_b32 s25, 1, 0
	s_cmp_ge_u32 s5, 0x1200
	s_cselect_b32 s35, 1, 0
	s_add_u32 s25, s25, s35
	s_cmp_ge_u32 s5, 0x1b00
	s_cselect_b32 s35, 1, 0
	s_add_u32 s25, s25, s35
	s_mul_i32 s27, s25, 0x900
	s_sub_u32 s27, s5, s27
	s_cmp_lt_u32 s27, 0x100
	s_cselect_b32 s20, 4, s25
	s_cmp_eq_u32 s20, s23
	s_cbranch_scc1 .Lnr6_0_0_same
	s_mov_b32 s23, s20
	s_mul_i32 s35, s20, 0xc000
	s_add_u32 s42, s64, s35
	s_addc_u32 s43, s65, 0
	s_add_u32 s44, s42, 0x1000
	s_addc_u32 s45, s43, 0
	global_load_dwordx4 v[52:55], v1, s[42:43] offset:0
	global_load_dwordx4 v[56:59], v1, s[42:43] offset:16
	global_load_dwordx4 v[60:63], v1, s[42:43] offset:2048
	global_load_dwordx4 v[64:67], v1, s[42:43] offset:2064
	global_load_dwordx4 v[68:71], v1, s[44:45] offset:0
	global_load_dwordx4 v[72:75], v1, s[44:45] offset:16
	global_load_dwordx4 v[76:79], v1, s[44:45] offset:2048
	global_load_dwordx4 v[80:83], v1, s[44:45] offset:2064
	s_add_u32 s42, s42, 0x2000
	s_addc_u32 s43, s43, 0
	s_add_u32 s44, s44, 0x2000
	s_addc_u32 s45, s45, 0
	global_load_dwordx4 v[84:87], v1, s[42:43] offset:0
	global_load_dwordx4 v[88:91], v1, s[42:43] offset:16
	global_load_dwordx4 v[92:95], v1, s[42:43] offset:2048
	global_load_dwordx4 v[96:99], v1, s[42:43] offset:2064
	global_load_dwordx4 v[100:103], v1, s[44:45] offset:0
	global_load_dwordx4 v[104:107], v1, s[44:45] offset:16
	global_load_dwordx4 v[108:111], v1, s[44:45] offset:2048
	global_load_dwordx4 v[112:115], v1, s[44:45] offset:2064
	s_waitcnt vmcnt(0)
	v_add_f32_e32 v84, 1.0, v84
	v_add_f32_e32 v85, 1.0, v85
	v_add_f32_e32 v86, 1.0, v86
	v_add_f32_e32 v87, 1.0, v87
	v_add_f32_e32 v88, 1.0, v88
	v_add_f32_e32 v89, 1.0, v89
	v_add_f32_e32 v90, 1.0, v90
	v_add_f32_e32 v91, 1.0, v91
	v_add_f32_e32 v92, 1.0, v92
	v_add_f32_e32 v93, 1.0, v93
	v_add_f32_e32 v94, 1.0, v94
	v_add_f32_e32 v95, 1.0, v95
	v_add_f32_e32 v96, 1.0, v96
	v_add_f32_e32 v97, 1.0, v97
	v_add_f32_e32 v98, 1.0, v98
	v_add_f32_e32 v99, 1.0, v99
	v_add_f32_e32 v100, 1.0, v100
	v_add_f32_e32 v101, 1.0, v101
	v_add_f32_e32 v102, 1.0, v102
	v_add_f32_e32 v103, 1.0, v103
	v_add_f32_e32 v104, 1.0, v104
	v_add_f32_e32 v105, 1.0, v105
	v_add_f32_e32 v106, 1.0, v106
	v_add_f32_e32 v107, 1.0, v107
	v_add_f32_e32 v108, 1.0, v108
	v_add_f32_e32 v109, 1.0, v109
	v_add_f32_e32 v110, 1.0, v110
	v_add_f32_e32 v111, 1.0, v111
	v_add_f32_e32 v112, 1.0, v112
	v_add_f32_e32 v113, 1.0, v113
	v_add_f32_e32 v114, 1.0, v114
	v_add_f32_e32 v115, 1.0, v115
.Lnr6_0_0_same:
	s_waitcnt vmcnt(12)
	v_mul_f32_e32 v11, v116, v116
	v_fmac_f32_e32 v11, v117, v117
	v_fmac_f32_e32 v11, v118, v118
	v_fmac_f32_e32 v11, v119, v119
	v_fmac_f32_e32 v11, v120, v120
	v_fmac_f32_e32 v11, v121, v121
	v_fmac_f32_e32 v11, v122, v122
	v_fmac_f32_e32 v11, v123, v123
	v_fmac_f32_e32 v11, v124, v124
	v_fmac_f32_e32 v11, v125, v125
	v_fmac_f32_e32 v11, v126, v126
	v_fmac_f32_e32 v11, v127, v127
	v_fmac_f32_e32 v11, v128, v128
	v_fmac_f32_e32 v11, v129, v129
	v_fmac_f32_e32 v11, v130, v130
	v_fmac_f32_e32 v11, v131, v131
	v_fmac_f32_e32 v11, v132, v132
	v_fmac_f32_e32 v11, v133, v133
	v_fmac_f32_e32 v11, v134, v134
	v_fmac_f32_e32 v11, v135, v135
	v_fmac_f32_e32 v11, v136, v136
	v_fmac_f32_e32 v11, v137, v137
	v_fmac_f32_e32 v11, v138, v138
	v_fmac_f32_e32 v11, v139, v139
	v_fmac_f32_e32 v11, v140, v140
	v_fmac_f32_e32 v11, v141, v141
	v_fmac_f32_e32 v11, v142, v142
	v_fmac_f32_e32 v11, v143, v143
	v_fmac_f32_e32 v11, v144, v144
	v_fmac_f32_e32 v11, v145, v145
	v_fmac_f32_e32 v11, v146, v146
	v_fmac_f32_e32 v11, v147, v147
	ds_bpermute_b32 v12, v3, v11
	s_waitcnt lgkmcnt(0)
	v_add_f32_e32 v11, v11, v12
	ds_bpermute_b32 v12, v4, v11
	s_waitcnt lgkmcnt(0)
	v_add_f32_e32 v11, v11, v12
	ds_bpermute_b32 v12, v5, v11
	s_waitcnt lgkmcnt(0)
	v_add_f32_e32 v11, v11, v12
	ds_bpermute_b32 v12, v6, v11
	s_waitcnt lgkmcnt(0)
	v_add_f32_e32 v11, v11, v12
	ds_bpermute_b32 v12, v7, v11
	s_waitcnt lgkmcnt(0)
	v_add_f32_e32 v11, v11, v12
	ds_bpermute_b32 v12, v8, v11
	s_waitcnt lgkmcnt(0)
	v_add_f32_e32 v11, v11, v12
	v_fmamk_f32 v11, v11, 0x3a000000, v9
	v_mul_f32_e32 v13, 0x4f800000, v11
	v_cmp_gt_f32_e32 vcc, 0xf800000, v11
	s_nop 1
	v_cndmask_b32_e32 v11, v11, v13, vcc
	v_sqrt_f32_e32 v13, v11
	s_nop 0
	v_add_u32_e32 v14, -1, v13
	v_add_u32_e32 v15, 1, v13
	v_fma_f32 v16, -v14, v13, v11
	v_fma_f32 v17, -v15, v13, v11
	v_cmp_ge_f32_e64 s[0:1], 0, v16
	s_nop 1
	v_cndmask_b32_e64 v13, v13, v14, s[0:1]
	v_cmp_lt_f32_e64 s[0:1], 0, v17
	s_nop 1
	v_cndmask_b32_e64 v13, v13, v15, s[0:1]
	v_mul_f32_e32 v14, 0x37800000, v13
	v_cndmask_b32_e32 v13, v13, v14, vcc
	v_cmp_class_f32_e32 vcc, v11, v10
	s_nop 1
	v_cndmask_b32_e32 v11, v13, v11, vcc
	v_div_scale_f32 v13, s[0:1], v11, v11, 1.0
	v_rcp_f32_e32 v15, v13
	v_div_scale_f32 v14, vcc, 1.0, v11, 1.0
	v_fma_f32 v16, -v13, v15, 1.0
	v_fmac_f32_e32 v15, v16, v15
	v_mul_f32_e32 v16, v14, v15
	v_fma_f32 v17, -v13, v16, v14
	v_fmac_f32_e32 v16, v17, v15
	v_fma_f32 v13, -v13, v16, v14
	v_div_fmas_f32 v13, v13, v15, v16
	v_div_fixup_f32 v11, v13, v11, 1.0
	s_lshl_b32 s35, s5, 12
	s_add_u32 s56, s62, s35
	s_addc_u32 s57, s63, 0
	v_mul_f32_e32 v116, v116, v11
	v_mul_f32_e32 v116, v20, v116
	v_fma_f32 v116, v84, v116, v52
	v_mul_f32_e32 v117, v117, v11
	v_mul_f32_e32 v117, v21, v117
	v_fma_f32 v117, v85, v117, v53
	v_mul_f32_e32 v118, v118, v11
	v_mul_f32_e32 v118, v22, v118
	v_fma_f32 v118, v86, v118, v54
	v_mul_f32_e32 v119, v119, v11
	v_mul_f32_e32 v119, v23, v119
	v_fma_f32 v119, v87, v119, v55
	v_mul_f32_e32 v120, v120, v11
	v_mul_f32_e32 v120, v24, v120
	v_fma_f32 v120, v88, v120, v56
	v_mul_f32_e32 v121, v121, v11
	v_mul_f32_e32 v121, v25, v121
	v_fma_f32 v121, v89, v121, v57
	v_mul_f32_e32 v122, v122, v11
	v_mul_f32_e32 v122, v26, v122
	v_fma_f32 v122, v90, v122, v58
	v_mul_f32_e32 v123, v123, v11
	v_mul_f32_e32 v123, v27, v123
	v_fma_f32 v123, v91, v123, v59
	v_cvt_pk_bf16_f32 v180, v116, v117
	v_cvt_pk_bf16_f32 v181, v118, v119
	v_cvt_pk_bf16_f32 v182, v120, v121
	v_cvt_pk_bf16_f32 v183, v122, v123
	global_store_dwordx4 v2, v[180:183], s[56:57] offset:0 sc1
	v_mul_f32_e32 v124, v124, v11
	v_mul_f32_e32 v124, v28, v124
	v_fma_f32 v124, v92, v124, v60
	v_mul_f32_e32 v125, v125, v11
	v_mul_f32_e32 v125, v29, v125
	v_fma_f32 v125, v93, v125, v61
	v_mul_f32_e32 v126, v126, v11
	v_mul_f32_e32 v126, v30, v126
	v_fma_f32 v126, v94, v126, v62
	v_mul_f32_e32 v127, v127, v11
	v_mul_f32_e32 v127, v31, v127
	v_fma_f32 v127, v95, v127, v63
	v_mul_f32_e32 v128, v128, v11
	v_mul_f32_e32 v128, v32, v128
	v_fma_f32 v128, v96, v128, v64
	v_mul_f32_e32 v129, v129, v11
	v_mul_f32_e32 v129, v33, v129
	v_fma_f32 v129, v97, v129, v65
	v_mul_f32_e32 v130, v130, v11
	v_mul_f32_e32 v130, v34, v130
	v_fma_f32 v130, v98, v130, v66
	v_mul_f32_e32 v131, v131, v11
	v_mul_f32_e32 v131, v35, v131
	v_fma_f32 v131, v99, v131, v67
	v_cvt_pk_bf16_f32 v184, v124, v125
	v_cvt_pk_bf16_f32 v185, v126, v127
	v_cvt_pk_bf16_f32 v186, v128, v129
	v_cvt_pk_bf16_f32 v187, v130, v131
	global_store_dwordx4 v2, v[184:187], s[56:57] offset:1024 sc1
	v_mul_f32_e32 v132, v132, v11
	v_mul_f32_e32 v132, v36, v132
	v_fma_f32 v132, v100, v132, v68
	v_mul_f32_e32 v133, v133, v11
	v_mul_f32_e32 v133, v37, v133
	v_fma_f32 v133, v101, v133, v69
	v_mul_f32_e32 v134, v134, v11
	v_mul_f32_e32 v134, v38, v134
	v_fma_f32 v134, v102, v134, v70
	v_mul_f32_e32 v135, v135, v11
	v_mul_f32_e32 v135, v39, v135
	v_fma_f32 v135, v103, v135, v71
	v_mul_f32_e32 v136, v136, v11
	v_mul_f32_e32 v136, v40, v136
	v_fma_f32 v136, v104, v136, v72
	v_mul_f32_e32 v137, v137, v11
	v_mul_f32_e32 v137, v41, v137
	v_fma_f32 v137, v105, v137, v73
	v_mul_f32_e32 v138, v138, v11
	v_mul_f32_e32 v138, v42, v138
	v_fma_f32 v138, v106, v138, v74
	v_mul_f32_e32 v139, v139, v11
	v_mul_f32_e32 v139, v43, v139
	v_fma_f32 v139, v107, v139, v75
	v_cvt_pk_bf16_f32 v188, v132, v133
	v_cvt_pk_bf16_f32 v189, v134, v135
	v_cvt_pk_bf16_f32 v190, v136, v137
	v_cvt_pk_bf16_f32 v191, v138, v139
	global_store_dwordx4 v2, v[188:191], s[56:57] offset:2048 sc1
	v_mul_f32_e32 v140, v140, v11
	v_mul_f32_e32 v140, v44, v140
	v_fma_f32 v140, v108, v140, v76
	v_mul_f32_e32 v141, v141, v11
	v_mul_f32_e32 v141, v45, v141
	v_fma_f32 v141, v109, v141, v77
	v_mul_f32_e32 v142, v142, v11
	v_mul_f32_e32 v142, v46, v142
	v_fma_f32 v142, v110, v142, v78
	v_mul_f32_e32 v143, v143, v11
	v_mul_f32_e32 v143, v47, v143
	v_fma_f32 v143, v111, v143, v79
	v_mul_f32_e32 v144, v144, v11
	v_mul_f32_e32 v144, v48, v144
	v_fma_f32 v144, v112, v144, v80
	v_mul_f32_e32 v145, v145, v11
	v_mul_f32_e32 v145, v49, v145
	v_fma_f32 v145, v113, v145, v81
	v_mul_f32_e32 v146, v146, v11
	v_mul_f32_e32 v146, v50, v146
	v_fma_f32 v146, v114, v146, v82
	v_mul_f32_e32 v147, v147, v11
	v_mul_f32_e32 v147, v51, v147
	v_fma_f32 v147, v115, v147, v83
	v_cvt_pk_bf16_f32 v192, v140, v141
	v_cvt_pk_bf16_f32 v193, v142, v143
	v_cvt_pk_bf16_f32 v194, v144, v145
	v_cvt_pk_bf16_f32 v195, v146, v147
	global_store_dwordx4 v2, v[192:195], s[56:57] offset:3072 sc1
	s_add_u32 s5, s5, 1
	s_add_u32 s31, s5, 1
	s_cmp_ge_u32 s31, s16
	s_cbranch_scc1 .Lnr6_last1
	s_lshl_b32 s35, s31, 13
	s_add_u32 s2, s58, s35
	s_addc_u32 s3, s59, 0
	s_add_u32 s6, s2, 0x1000
	s_addc_u32 s7, s3, 0
	global_load_dwordx4 v[116:119], v1, s[2:3] offset:0
	global_load_dwordx4 v[120:123], v1, s[2:3] offset:16
	global_load_dwordx4 v[124:127], v1, s[2:3] offset:2048
	global_load_dwordx4 v[128:131], v1, s[2:3] offset:2064
	global_load_dwordx4 v[132:135], v1, s[6:7] offset:0
	global_load_dwordx4 v[136:139], v1, s[6:7] offset:16
	global_load_dwordx4 v[140:143], v1, s[6:7] offset:2048
	global_load_dwordx4 v[144:147], v1, s[6:7] offset:2064
	s_cmp_ge_u32 s5, 0x900
	s_cselect_b32 s25, 1, 0
	s_cmp_ge_u32 s5, 0x1200
	s_cselect_b32 s35, 1, 0
	s_add_u32 s25, s25, s35
	s_cmp_ge_u32 s5, 0x1b00
	s_cselect_b32 s35, 1, 0
	s_add_u32 s25, s25, s35
	s_mul_i32 s27, s25, 0x900
	s_sub_u32 s27, s5, s27
	s_cmp_lt_u32 s27, 0x100
	s_cselect_b32 s20, 4, s25
	s_cmp_eq_u32 s20, s23
	s_cbranch_scc1 .Lnr6_1_0_same
	s_mov_b32 s23, s20
	s_mul_i32 s35, s20, 0xc000
	s_add_u32 s42, s64, s35
	s_addc_u32 s43, s65, 0
	s_add_u32 s44, s42, 0x1000
	s_addc_u32 s45, s43, 0
	global_load_dwordx4 v[52:55], v1, s[42:43] offset:0
	global_load_dwordx4 v[56:59], v1, s[42:43] offset:16
	global_load_dwordx4 v[60:63], v1, s[42:43] offset:2048
	global_load_dwordx4 v[64:67], v1, s[42:43] offset:2064
	global_load_dwordx4 v[68:71], v1, s[44:45] offset:0
	global_load_dwordx4 v[72:75], v1, s[44:45] offset:16
	global_load_dwordx4 v[76:79], v1, s[44:45] offset:2048
	global_load_dwordx4 v[80:83], v1, s[44:45] offset:2064
	s_add_u32 s42, s42, 0x2000
	s_addc_u32 s43, s43, 0
	s_add_u32 s44, s44, 0x2000
	s_addc_u32 s45, s45, 0
	global_load_dwordx4 v[84:87], v1, s[42:43] offset:0
	global_load_dwordx4 v[88:91], v1, s[42:43] offset:16
	global_load_dwordx4 v[92:95], v1, s[42:43] offset:2048
	global_load_dwordx4 v[96:99], v1, s[42:43] offset:2064
	global_load_dwordx4 v[100:103], v1, s[44:45] offset:0
	global_load_dwordx4 v[104:107], v1, s[44:45] offset:16
	global_load_dwordx4 v[108:111], v1, s[44:45] offset:2048
	global_load_dwordx4 v[112:115], v1, s[44:45] offset:2064
	s_waitcnt vmcnt(0)
	v_add_f32_e32 v84, 1.0, v84
	v_add_f32_e32 v85, 1.0, v85
	v_add_f32_e32 v86, 1.0, v86
	v_add_f32_e32 v87, 1.0, v87
	v_add_f32_e32 v88, 1.0, v88
	v_add_f32_e32 v89, 1.0, v89
	v_add_f32_e32 v90, 1.0, v90
	v_add_f32_e32 v91, 1.0, v91
	v_add_f32_e32 v92, 1.0, v92
	v_add_f32_e32 v93, 1.0, v93
	v_add_f32_e32 v94, 1.0, v94
	v_add_f32_e32 v95, 1.0, v95
	v_add_f32_e32 v96, 1.0, v96
	v_add_f32_e32 v97, 1.0, v97
	v_add_f32_e32 v98, 1.0, v98
	v_add_f32_e32 v99, 1.0, v99
	v_add_f32_e32 v100, 1.0, v100
	v_add_f32_e32 v101, 1.0, v101
	v_add_f32_e32 v102, 1.0, v102
	v_add_f32_e32 v103, 1.0, v103
	v_add_f32_e32 v104, 1.0, v104
	v_add_f32_e32 v105, 1.0, v105
	v_add_f32_e32 v106, 1.0, v106
	v_add_f32_e32 v107, 1.0, v107
	v_add_f32_e32 v108, 1.0, v108
	v_add_f32_e32 v109, 1.0, v109
	v_add_f32_e32 v110, 1.0, v110
	v_add_f32_e32 v111, 1.0, v111
	v_add_f32_e32 v112, 1.0, v112
	v_add_f32_e32 v113, 1.0, v113
	v_add_f32_e32 v114, 1.0, v114
	v_add_f32_e32 v115, 1.0, v115
.Lnr6_1_0_same:
	s_waitcnt vmcnt(12)
	v_mul_f32_e32 v11, v148, v148
	v_fmac_f32_e32 v11, v149, v149
	v_fmac_f32_e32 v11, v150, v150
	v_fmac_f32_e32 v11, v151, v151
	v_fmac_f32_e32 v11, v152, v152
	v_fmac_f32_e32 v11, v153, v153
	v_fmac_f32_e32 v11, v154, v154
	v_fmac_f32_e32 v11, v155, v155
	v_fmac_f32_e32 v11, v156, v156
	v_fmac_f32_e32 v11, v157, v157
	v_fmac_f32_e32 v11, v158, v158
	v_fmac_f32_e32 v11, v159, v159
	v_fmac_f32_e32 v11, v160, v160
	v_fmac_f32_e32 v11, v161, v161
	v_fmac_f32_e32 v11, v162, v162
	v_fmac_f32_e32 v11, v163, v163
	v_fmac_f32_e32 v11, v164, v164
	v_fmac_f32_e32 v11, v165, v165
	v_fmac_f32_e32 v11, v166, v166
	v_fmac_f32_e32 v11, v167, v167
	v_fmac_f32_e32 v11, v168, v168
	v_fmac_f32_e32 v11, v169, v169
	v_fmac_f32_e32 v11, v170, v170
	v_fmac_f32_e32 v11, v171, v171
	v_fmac_f32_e32 v11, v172, v172
	v_fmac_f32_e32 v11, v173, v173
	v_fmac_f32_e32 v11, v174, v174
	v_fmac_f32_e32 v11, v175, v175
	v_fmac_f32_e32 v11, v176, v176
	v_fmac_f32_e32 v11, v177, v177
	v_fmac_f32_e32 v11, v178, v178
	v_fmac_f32_e32 v11, v179, v179
	ds_bpermute_b32 v12, v3, v11
	s_waitcnt lgkmcnt(0)
	v_add_f32_e32 v11, v11, v12
	ds_bpermute_b32 v12, v4, v11
	s_waitcnt lgkmcnt(0)
	v_add_f32_e32 v11, v11, v12
	ds_bpermute_b32 v12, v5, v11
	s_waitcnt lgkmcnt(0)
	v_add_f32_e32 v11, v11, v12
	ds_bpermute_b32 v12, v6, v11
	s_waitcnt lgkmcnt(0)
	v_add_f32_e32 v11, v11, v12
	ds_bpermute_b32 v12, v7, v11
	s_waitcnt lgkmcnt(0)
	v_add_f32_e32 v11, v11, v12
	ds_bpermute_b32 v12, v8, v11
	s_waitcnt lgkmcnt(0)
	v_add_f32_e32 v11, v11, v12
	v_fmamk_f32 v11, v11, 0x3a000000, v9
	v_mul_f32_e32 v13, 0x4f800000, v11
	v_cmp_gt_f32_e32 vcc, 0xf800000, v11
	s_nop 1
	v_cndmask_b32_e32 v11, v11, v13, vcc
	v_sqrt_f32_e32 v13, v11
	s_nop 0
	v_add_u32_e32 v14, -1, v13
	v_add_u32_e32 v15, 1, v13
	v_fma_f32 v16, -v14, v13, v11
	v_fma_f32 v17, -v15, v13, v11
	v_cmp_ge_f32_e64 s[0:1], 0, v16
	s_nop 1
	v_cndmask_b32_e64 v13, v13, v14, s[0:1]
	v_cmp_lt_f32_e64 s[0:1], 0, v17
	s_nop 1
	v_cndmask_b32_e64 v13, v13, v15, s[0:1]
	v_mul_f32_e32 v14, 0x37800000, v13
	v_cndmask_b32_e32 v13, v13, v14, vcc
	v_cmp_class_f32_e32 vcc, v11, v10
	s_nop 1
	v_cndmask_b32_e32 v11, v13, v11, vcc
	v_div_scale_f32 v13, s[0:1], v11, v11, 1.0
	v_rcp_f32_e32 v15, v13
	v_div_scale_f32 v14, vcc, 1.0, v11, 1.0
	v_fma_f32 v16, -v13, v15, 1.0
	v_fmac_f32_e32 v15, v16, v15
	v_mul_f32_e32 v16, v14, v15
	v_fma_f32 v17, -v13, v16, v14
	v_fmac_f32_e32 v16, v17, v15
	v_fma_f32 v13, -v13, v16, v14
	v_div_fmas_f32 v13, v13, v15, v16
	v_div_fixup_f32 v11, v13, v11, 1.0
	s_lshl_b32 s35, s5, 12
	s_add_u32 s56, s62, s35
	s_addc_u32 s57, s63, 0
	v_mul_f32_e32 v148, v148, v11
	v_mul_f32_e32 v148, v20, v148
	v_fma_f32 v148, v84, v148, v52
	v_mul_f32_e32 v149, v149, v11
	v_mul_f32_e32 v149, v21, v149
	v_fma_f32 v149, v85, v149, v53
	v_mul_f32_e32 v150, v150, v11
	v_mul_f32_e32 v150, v22, v150
	v_fma_f32 v150, v86, v150, v54
	v_mul_f32_e32 v151, v151, v11
	v_mul_f32_e32 v151, v23, v151
	v_fma_f32 v151, v87, v151, v55
	v_mul_f32_e32 v152, v152, v11
	v_mul_f32_e32 v152, v24, v152
	v_fma_f32 v152, v88, v152, v56
	v_mul_f32_e32 v153, v153, v11
	v_mul_f32_e32 v153, v25, v153
	v_fma_f32 v153, v89, v153, v57
	v_mul_f32_e32 v154, v154, v11
	v_mul_f32_e32 v154, v26, v154
	v_fma_f32 v154, v90, v154, v58
	v_mul_f32_e32 v155, v155, v11
	v_mul_f32_e32 v155, v27, v155
	v_fma_f32 v155, v91, v155, v59
	v_cvt_pk_bf16_f32 v180, v148, v149
	v_cvt_pk_bf16_f32 v181, v150, v151
	v_cvt_pk_bf16_f32 v182, v152, v153
	v_cvt_pk_bf16_f32 v183, v154, v155
	global_store_dwordx4 v2, v[180:183], s[56:57] offset:0 sc1
	v_mul_f32_e32 v156, v156, v11
	v_mul_f32_e32 v156, v28, v156
	v_fma_f32 v156, v92, v156, v60
	v_mul_f32_e32 v157, v157, v11
	v_mul_f32_e32 v157, v29, v157
	v_fma_f32 v157, v93, v157, v61
	v_mul_f32_e32 v158, v158, v11
	v_mul_f32_e32 v158, v30, v158
	v_fma_f32 v158, v94, v158, v62
	v_mul_f32_e32 v159, v159, v11
	v_mul_f32_e32 v159, v31, v159
	v_fma_f32 v159, v95, v159, v63
	v_mul_f32_e32 v160, v160, v11
	v_mul_f32_e32 v160, v32, v160
	v_fma_f32 v160, v96, v160, v64
	v_mul_f32_e32 v161, v161, v11
	v_mul_f32_e32 v161, v33, v161
	v_fma_f32 v161, v97, v161, v65
	v_mul_f32_e32 v162, v162, v11
	v_mul_f32_e32 v162, v34, v162
	v_fma_f32 v162, v98, v162, v66
	v_mul_f32_e32 v163, v163, v11
	v_mul_f32_e32 v163, v35, v163
	v_fma_f32 v163, v99, v163, v67
	v_cvt_pk_bf16_f32 v184, v156, v157
	v_cvt_pk_bf16_f32 v185, v158, v159
	v_cvt_pk_bf16_f32 v186, v160, v161
	v_cvt_pk_bf16_f32 v187, v162, v163
	global_store_dwordx4 v2, v[184:187], s[56:57] offset:1024 sc1
	v_mul_f32_e32 v164, v164, v11
	v_mul_f32_e32 v164, v36, v164
	v_fma_f32 v164, v100, v164, v68
	v_mul_f32_e32 v165, v165, v11
	v_mul_f32_e32 v165, v37, v165
	v_fma_f32 v165, v101, v165, v69
	v_mul_f32_e32 v166, v166, v11
	v_mul_f32_e32 v166, v38, v166
	v_fma_f32 v166, v102, v166, v70
	v_mul_f32_e32 v167, v167, v11
	v_mul_f32_e32 v167, v39, v167
	v_fma_f32 v167, v103, v167, v71
	v_mul_f32_e32 v168, v168, v11
	v_mul_f32_e32 v168, v40, v168
	v_fma_f32 v168, v104, v168, v72
	v_mul_f32_e32 v169, v169, v11
	v_mul_f32_e32 v169, v41, v169
	v_fma_f32 v169, v105, v169, v73
	v_mul_f32_e32 v170, v170, v11
	v_mul_f32_e32 v170, v42, v170
	v_fma_f32 v170, v106, v170, v74
	v_mul_f32_e32 v171, v171, v11
	v_mul_f32_e32 v171, v43, v171
	v_fma_f32 v171, v107, v171, v75
	v_cvt_pk_bf16_f32 v188, v164, v165
	v_cvt_pk_bf16_f32 v189, v166, v167
	v_cvt_pk_bf16_f32 v190, v168, v169
	v_cvt_pk_bf16_f32 v191, v170, v171
	global_store_dwordx4 v2, v[188:191], s[56:57] offset:2048 sc1
	v_mul_f32_e32 v172, v172, v11
	v_mul_f32_e32 v172, v44, v172
	v_fma_f32 v172, v108, v172, v76
	v_mul_f32_e32 v173, v173, v11
	v_mul_f32_e32 v173, v45, v173
	v_fma_f32 v173, v109, v173, v77
	v_mul_f32_e32 v174, v174, v11
	v_mul_f32_e32 v174, v46, v174
	v_fma_f32 v174, v110, v174, v78
	v_mul_f32_e32 v175, v175, v11
	v_mul_f32_e32 v175, v47, v175
	v_fma_f32 v175, v111, v175, v79
	v_mul_f32_e32 v176, v176, v11
	v_mul_f32_e32 v176, v48, v176
	v_fma_f32 v176, v112, v176, v80
	v_mul_f32_e32 v177, v177, v11
	v_mul_f32_e32 v177, v49, v177
	v_fma_f32 v177, v113, v177, v81
	v_mul_f32_e32 v178, v178, v11
	v_mul_f32_e32 v178, v50, v178
	v_fma_f32 v178, v114, v178, v82
	v_mul_f32_e32 v179, v179, v11
	v_mul_f32_e32 v179, v51, v179
	v_fma_f32 v179, v115, v179, v83
	v_cvt_pk_bf16_f32 v192, v172, v173
	v_cvt_pk_bf16_f32 v193, v174, v175
	v_cvt_pk_bf16_f32 v194, v176, v177
	v_cvt_pk_bf16_f32 v195, v178, v179
	global_store_dwordx4 v2, v[192:195], s[56:57] offset:3072 sc1
	s_add_u32 s5, s5, 1
	s_branch .Lnr6_loop
.Lnr6_last0:
	s_cmp_ge_u32 s5, 0x900
	s_cselect_b32 s25, 1, 0
	s_cmp_ge_u32 s5, 0x1200
	s_cselect_b32 s35, 1, 0
	s_add_u32 s25, s25, s35
	s_cmp_ge_u32 s5, 0x1b00
	s_cselect_b32 s35, 1, 0
	s_add_u32 s25, s25, s35
	s_mul_i32 s27, s25, 0x900
	s_sub_u32 s27, s5, s27
	s_cmp_lt_u32 s27, 0x100
	s_cselect_b32 s20, 4, s25
	s_cmp_eq_u32 s20, s23
	s_cbranch_scc1 .Lnr6_0_1_same
	s_mov_b32 s23, s20
	s_mul_i32 s35, s20, 0xc000
	s_add_u32 s42, s64, s35
	s_addc_u32 s43, s65, 0
	s_add_u32 s44, s42, 0x1000
	s_addc_u32 s45, s43, 0
	global_load_dwordx4 v[52:55], v1, s[42:43] offset:0
	global_load_dwordx4 v[56:59], v1, s[42:43] offset:16
	global_load_dwordx4 v[60:63], v1, s[42:43] offset:2048
	global_load_dwordx4 v[64:67], v1, s[42:43] offset:2064
	global_load_dwordx4 v[68:71], v1, s[44:45] offset:0
	global_load_dwordx4 v[72:75], v1, s[44:45] offset:16
	global_load_dwordx4 v[76:79], v1, s[44:45] offset:2048
	global_load_dwordx4 v[80:83], v1, s[44:45] offset:2064
	s_add_u32 s42, s42, 0x2000
	s_addc_u32 s43, s43, 0
	s_add_u32 s44, s44, 0x2000
	s_addc_u32 s45, s45, 0
	global_load_dwordx4 v[84:87], v1, s[42:43] offset:0
	global_load_dwordx4 v[88:91], v1, s[42:43] offset:16
	global_load_dwordx4 v[92:95], v1, s[42:43] offset:2048
	global_load_dwordx4 v[96:99], v1, s[42:43] offset:2064
	global_load_dwordx4 v[100:103], v1, s[44:45] offset:0
	global_load_dwordx4 v[104:107], v1, s[44:45] offset:16
	global_load_dwordx4 v[108:111], v1, s[44:45] offset:2048
	global_load_dwordx4 v[112:115], v1, s[44:45] offset:2064
	s_waitcnt vmcnt(0)
	v_add_f32_e32 v84, 1.0, v84
	v_add_f32_e32 v85, 1.0, v85
	v_add_f32_e32 v86, 1.0, v86
	v_add_f32_e32 v87, 1.0, v87
	v_add_f32_e32 v88, 1.0, v88
	v_add_f32_e32 v89, 1.0, v89
	v_add_f32_e32 v90, 1.0, v90
	v_add_f32_e32 v91, 1.0, v91
	v_add_f32_e32 v92, 1.0, v92
	v_add_f32_e32 v93, 1.0, v93
	v_add_f32_e32 v94, 1.0, v94
	v_add_f32_e32 v95, 1.0, v95
	v_add_f32_e32 v96, 1.0, v96
	v_add_f32_e32 v97, 1.0, v97
	v_add_f32_e32 v98, 1.0, v98
	v_add_f32_e32 v99, 1.0, v99
	v_add_f32_e32 v100, 1.0, v100
	v_add_f32_e32 v101, 1.0, v101
	v_add_f32_e32 v102, 1.0, v102
	v_add_f32_e32 v103, 1.0, v103
	v_add_f32_e32 v104, 1.0, v104
	v_add_f32_e32 v105, 1.0, v105
	v_add_f32_e32 v106, 1.0, v106
	v_add_f32_e32 v107, 1.0, v107
	v_add_f32_e32 v108, 1.0, v108
	v_add_f32_e32 v109, 1.0, v109
	v_add_f32_e32 v110, 1.0, v110
	v_add_f32_e32 v111, 1.0, v111
	v_add_f32_e32 v112, 1.0, v112
	v_add_f32_e32 v113, 1.0, v113
	v_add_f32_e32 v114, 1.0, v114
	v_add_f32_e32 v115, 1.0, v115
.Lnr6_0_1_same:
	s_waitcnt vmcnt(4)
	v_mul_f32_e32 v11, v116, v116
	v_fmac_f32_e32 v11, v117, v117
	v_fmac_f32_e32 v11, v118, v118
	v_fmac_f32_e32 v11, v119, v119
	v_fmac_f32_e32 v11, v120, v120
	v_fmac_f32_e32 v11, v121, v121
	v_fmac_f32_e32 v11, v122, v122
	v_fmac_f32_e32 v11, v123, v123
	v_fmac_f32_e32 v11, v124, v124
	v_fmac_f32_e32 v11, v125, v125
	v_fmac_f32_e32 v11, v126, v126
	v_fmac_f32_e32 v11, v127, v127
	v_fmac_f32_e32 v11, v128, v128
	v_fmac_f32_e32 v11, v129, v129
	v_fmac_f32_e32 v11, v130, v130
	v_fmac_f32_e32 v11, v131, v131
	v_fmac_f32_e32 v11, v132, v132
	v_fmac_f32_e32 v11, v133, v133
	v_fmac_f32_e32 v11, v134, v134
	v_fmac_f32_e32 v11, v135, v135
	v_fmac_f32_e32 v11, v136, v136
	v_fmac_f32_e32 v11, v137, v137
	v_fmac_f32_e32 v11, v138, v138
	v_fmac_f32_e32 v11, v139, v139
	v_fmac_f32_e32 v11, v140, v140
	v_fmac_f32_e32 v11, v141, v141
	v_fmac_f32_e32 v11, v142, v142
	v_fmac_f32_e32 v11, v143, v143
	v_fmac_f32_e32 v11, v144, v144
	v_fmac_f32_e32 v11, v145, v145
	v_fmac_f32_e32 v11, v146, v146
	v_fmac_f32_e32 v11, v147, v147
	ds_bpermute_b32 v12, v3, v11
	s_waitcnt lgkmcnt(0)
	v_add_f32_e32 v11, v11, v12
	ds_bpermute_b32 v12, v4, v11
	s_waitcnt lgkmcnt(0)
	v_add_f32_e32 v11, v11, v12
	ds_bpermute_b32 v12, v5, v11
	s_waitcnt lgkmcnt(0)
	v_add_f32_e32 v11, v11, v12
	ds_bpermute_b32 v12, v6, v11
	s_waitcnt lgkmcnt(0)
	v_add_f32_e32 v11, v11, v12
	ds_bpermute_b32 v12, v7, v11
	s_waitcnt lgkmcnt(0)
	v_add_f32_e32 v11, v11, v12
	ds_bpermute_b32 v12, v8, v11
	s_waitcnt lgkmcnt(0)
	v_add_f32_e32 v11, v11, v12
	v_fmamk_f32 v11, v11, 0x3a000000, v9
	v_mul_f32_e32 v13, 0x4f800000, v11
	v_cmp_gt_f32_e32 vcc, 0xf800000, v11
	s_nop 1
	v_cndmask_b32_e32 v11, v11, v13, vcc
	v_sqrt_f32_e32 v13, v11
	s_nop 0
	v_add_u32_e32 v14, -1, v13
	v_add_u32_e32 v15, 1, v13
	v_fma_f32 v16, -v14, v13, v11
	v_fma_f32 v17, -v15, v13, v11
	v_cmp_ge_f32_e64 s[0:1], 0, v16
	s_nop 1
	v_cndmask_b32_e64 v13, v13, v14, s[0:1]
	v_cmp_lt_f32_e64 s[0:1], 0, v17
	s_nop 1
	v_cndmask_b32_e64 v13, v13, v15, s[0:1]
	v_mul_f32_e32 v14, 0x37800000, v13
	v_cndmask_b32_e32 v13, v13, v14, vcc
	v_cmp_class_f32_e32 vcc, v11, v10
	s_nop 1
	v_cndmask_b32_e32 v11, v13, v11, vcc
	v_div_scale_f32 v13, s[0:1], v11, v11, 1.0
	v_rcp_f32_e32 v15, v13
	v_div_scale_f32 v14, vcc, 1.0, v11, 1.0
	v_fma_f32 v16, -v13, v15, 1.0
	v_fmac_f32_e32 v15, v16, v15
	v_mul_f32_e32 v16, v14, v15
	v_fma_f32 v17, -v13, v16, v14
	v_fmac_f32_e32 v16, v17, v15
	v_fma_f32 v13, -v13, v16, v14
	v_div_fmas_f32 v13, v13, v15, v16
	v_div_fixup_f32 v11, v13, v11, 1.0
	s_lshl_b32 s35, s5, 12
	s_add_u32 s56, s62, s35
	s_addc_u32 s57, s63, 0
	v_mul_f32_e32 v116, v116, v11
	v_mul_f32_e32 v116, v20, v116
	v_fma_f32 v116, v84, v116, v52
	v_mul_f32_e32 v117, v117, v11
	v_mul_f32_e32 v117, v21, v117
	v_fma_f32 v117, v85, v117, v53
	v_mul_f32_e32 v118, v118, v11
	v_mul_f32_e32 v118, v22, v118
	v_fma_f32 v118, v86, v118, v54
	v_mul_f32_e32 v119, v119, v11
	v_mul_f32_e32 v119, v23, v119
	v_fma_f32 v119, v87, v119, v55
	v_mul_f32_e32 v120, v120, v11
	v_mul_f32_e32 v120, v24, v120
	v_fma_f32 v120, v88, v120, v56
	v_mul_f32_e32 v121, v121, v11
	v_mul_f32_e32 v121, v25, v121
	v_fma_f32 v121, v89, v121, v57
	v_mul_f32_e32 v122, v122, v11
	v_mul_f32_e32 v122, v26, v122
	v_fma_f32 v122, v90, v122, v58
	v_mul_f32_e32 v123, v123, v11
	v_mul_f32_e32 v123, v27, v123
	v_fma_f32 v123, v91, v123, v59
	v_cvt_pk_bf16_f32 v180, v116, v117
	v_cvt_pk_bf16_f32 v181, v118, v119
	v_cvt_pk_bf16_f32 v182, v120, v121
	v_cvt_pk_bf16_f32 v183, v122, v123
	global_store_dwordx4 v2, v[180:183], s[56:57] offset:0 sc1
	v_mul_f32_e32 v124, v124, v11
	v_mul_f32_e32 v124, v28, v124
	v_fma_f32 v124, v92, v124, v60
	v_mul_f32_e32 v125, v125, v11
	v_mul_f32_e32 v125, v29, v125
	v_fma_f32 v125, v93, v125, v61
	v_mul_f32_e32 v126, v126, v11
	v_mul_f32_e32 v126, v30, v126
	v_fma_f32 v126, v94, v126, v62
	v_mul_f32_e32 v127, v127, v11
	v_mul_f32_e32 v127, v31, v127
	v_fma_f32 v127, v95, v127, v63
	v_mul_f32_e32 v128, v128, v11
	v_mul_f32_e32 v128, v32, v128
	v_fma_f32 v128, v96, v128, v64
	v_mul_f32_e32 v129, v129, v11
	v_mul_f32_e32 v129, v33, v129
	v_fma_f32 v129, v97, v129, v65
	v_mul_f32_e32 v130, v130, v11
	v_mul_f32_e32 v130, v34, v130
	v_fma_f32 v130, v98, v130, v66
	v_mul_f32_e32 v131, v131, v11
	v_mul_f32_e32 v131, v35, v131
	v_fma_f32 v131, v99, v131, v67
	v_cvt_pk_bf16_f32 v184, v124, v125
	v_cvt_pk_bf16_f32 v185, v126, v127
	v_cvt_pk_bf16_f32 v186, v128, v129
	v_cvt_pk_bf16_f32 v187, v130, v131
	global_store_dwordx4 v2, v[184:187], s[56:57] offset:1024 sc1
	v_mul_f32_e32 v132, v132, v11
	v_mul_f32_e32 v132, v36, v132
	v_fma_f32 v132, v100, v132, v68
	v_mul_f32_e32 v133, v133, v11
	v_mul_f32_e32 v133, v37, v133
	v_fma_f32 v133, v101, v133, v69
	v_mul_f32_e32 v134, v134, v11
	v_mul_f32_e32 v134, v38, v134
	v_fma_f32 v134, v102, v134, v70
	v_mul_f32_e32 v135, v135, v11
	v_mul_f32_e32 v135, v39, v135
	v_fma_f32 v135, v103, v135, v71
	v_mul_f32_e32 v136, v136, v11
	v_mul_f32_e32 v136, v40, v136
	v_fma_f32 v136, v104, v136, v72
	v_mul_f32_e32 v137, v137, v11
	v_mul_f32_e32 v137, v41, v137
	v_fma_f32 v137, v105, v137, v73
	v_mul_f32_e32 v138, v138, v11
	v_mul_f32_e32 v138, v42, v138
	v_fma_f32 v138, v106, v138, v74
	v_mul_f32_e32 v139, v139, v11
	v_mul_f32_e32 v139, v43, v139
	v_fma_f32 v139, v107, v139, v75
	v_cvt_pk_bf16_f32 v188, v132, v133
	v_cvt_pk_bf16_f32 v189, v134, v135
	v_cvt_pk_bf16_f32 v190, v136, v137
	v_cvt_pk_bf16_f32 v191, v138, v139
	global_store_dwordx4 v2, v[188:191], s[56:57] offset:2048 sc1
	v_mul_f32_e32 v140, v140, v11
	v_mul_f32_e32 v140, v44, v140
	v_fma_f32 v140, v108, v140, v76
	v_mul_f32_e32 v141, v141, v11
	v_mul_f32_e32 v141, v45, v141
	v_fma_f32 v141, v109, v141, v77
	v_mul_f32_e32 v142, v142, v11
	v_mul_f32_e32 v142, v46, v142
	v_fma_f32 v142, v110, v142, v78
	v_mul_f32_e32 v143, v143, v11
	v_mul_f32_e32 v143, v47, v143
	v_fma_f32 v143, v111, v143, v79
	v_mul_f32_e32 v144, v144, v11
	v_mul_f32_e32 v144, v48, v144
	v_fma_f32 v144, v112, v144, v80
	v_mul_f32_e32 v145, v145, v11
	v_mul_f32_e32 v145, v49, v145
	v_fma_f32 v145, v113, v145, v81
	v_mul_f32_e32 v146, v146, v11
	v_mul_f32_e32 v146, v50, v146
	v_fma_f32 v146, v114, v146, v82
	v_mul_f32_e32 v147, v147, v11
	v_mul_f32_e32 v147, v51, v147
	v_fma_f32 v147, v115, v147, v83
	v_cvt_pk_bf16_f32 v192, v140, v141
	v_cvt_pk_bf16_f32 v193, v142, v143
	v_cvt_pk_bf16_f32 v194, v144, v145
	v_cvt_pk_bf16_f32 v195, v146, v147
	global_store_dwordx4 v2, v[192:195], s[56:57] offset:3072 sc1
	s_branch .Lnr6_done

.Lnr6_1_1_same:
	s_waitcnt vmcnt(4)
	v_mul_f32_e32 v11, v148, v148
	v_fmac_f32_e32 v11, v149, v149
	v_fmac_f32_e32 v11, v150, v150
	v_fmac_f32_e32 v11, v151, v151
	v_fmac_f32_e32 v11, v152, v152
	v_fmac_f32_e32 v11, v153, v153
	v_fmac_f32_e32 v11, v154, v154
	v_fmac_f32_e32 v11, v155, v155
	v_fmac_f32_e32 v11, v156, v156
	v_fmac_f32_e32 v11, v157, v157
	v_fmac_f32_e32 v11, v158, v158
	v_fmac_f32_e32 v11, v159, v159
	v_fmac_f32_e32 v11, v160, v160
	v_fmac_f32_e32 v11, v161, v161
	v_fmac_f32_e32 v11, v162, v162
	v_fmac_f32_e32 v11, v163, v163
	v_fmac_f32_e32 v11, v164, v164
	v_fmac_f32_e32 v11, v165, v165
	v_fmac_f32_e32 v11, v166, v166
	v_fmac_f32_e32 v11, v167, v167
	v_fmac_f32_e32 v11, v168, v168
	v_fmac_f32_e32 v11, v169, v169
	v_fmac_f32_e32 v11, v170, v170
	v_fmac_f32_e32 v11, v171, v171
	v_fmac_f32_e32 v11, v172, v172
	v_fmac_f32_e32 v11, v173, v173
	v_fmac_f32_e32 v11, v174, v174
	v_fmac_f32_e32 v11, v175, v175
	v_fmac_f32_e32 v11, v176, v176
	v_fmac_f32_e32 v11, v177, v177
	v_fmac_f32_e32 v11, v178, v178
	v_fmac_f32_e32 v11, v179, v179
	ds_bpermute_b32 v12, v3, v11
	s_waitcnt lgkmcnt(0)
	v_add_f32_e32 v11, v11, v12
	ds_bpermute_b32 v12, v4, v11
	s_waitcnt lgkmcnt(0)
	v_add_f32_e32 v11, v11, v12
	ds_bpermute_b32 v12, v5, v11
	s_waitcnt lgkmcnt(0)
	v_add_f32_e32 v11, v11, v12
	ds_bpermute_b32 v12, v6, v11
	s_waitcnt lgkmcnt(0)
	v_add_f32_e32 v11, v11, v12
	ds_bpermute_b32 v12, v7, v11
	s_waitcnt lgkmcnt(0)
	v_add_f32_e32 v11, v11, v12
	ds_bpermute_b32 v12, v8, v11
	s_waitcnt lgkmcnt(0)
	v_add_f32_e32 v11, v11, v12
	v_fmamk_f32 v11, v11, 0x3a000000, v9
	v_mul_f32_e32 v13, 0x4f800000, v11
	v_cmp_gt_f32_e32 vcc, 0xf800000, v11
	s_nop 1
	v_cndmask_b32_e32 v11, v11, v13, vcc
	v_sqrt_f32_e32 v13, v11
	s_nop 0
	v_add_u32_e32 v14, -1, v13
	v_add_u32_e32 v15, 1, v13
	v_fma_f32 v16, -v14, v13, v11
	v_fma_f32 v17, -v15, v13, v11
	v_cmp_ge_f32_e64 s[0:1], 0, v16
	s_nop 1
	v_cndmask_b32_e64 v13, v13, v14, s[0:1]
	v_cmp_lt_f32_e64 s[0:1], 0, v17
	s_nop 1
	v_cndmask_b32_e64 v13, v13, v15, s[0:1]
	v_mul_f32_e32 v14, 0x37800000, v13
	v_cndmask_b32_e32 v13, v13, v14, vcc
	v_cmp_class_f32_e32 vcc, v11, v10
	s_nop 1
	v_cndmask_b32_e32 v11, v13, v11, vcc
	v_div_scale_f32 v13, s[0:1], v11, v11, 1.0
	v_rcp_f32_e32 v15, v13
	v_div_scale_f32 v14, vcc, 1.0, v11, 1.0
	v_fma_f32 v16, -v13, v15, 1.0
	v_fmac_f32_e32 v15, v16, v15
	v_mul_f32_e32 v16, v14, v15
	v_fma_f32 v17, -v13, v16, v14
	v_fmac_f32_e32 v16, v17, v15
	v_fma_f32 v13, -v13, v16, v14
	v_div_fmas_f32 v13, v13, v15, v16
	v_div_fixup_f32 v11, v13, v11, 1.0
	s_lshl_b32 s35, s5, 12
	s_add_u32 s56, s62, s35
	s_addc_u32 s57, s63, 0
	v_mul_f32_e32 v148, v148, v11
	v_mul_f32_e32 v148, v20, v148
	v_fma_f32 v148, v84, v148, v52
	v_mul_f32_e32 v149, v149, v11
	v_mul_f32_e32 v149, v21, v149
	v_fma_f32 v149, v85, v149, v53
	v_mul_f32_e32 v150, v150, v11
	v_mul_f32_e32 v150, v22, v150
	v_fma_f32 v150, v86, v150, v54
	v_mul_f32_e32 v151, v151, v11
	v_mul_f32_e32 v151, v23, v151
	v_fma_f32 v151, v87, v151, v55
	v_mul_f32_e32 v152, v152, v11
	v_mul_f32_e32 v152, v24, v152
	v_fma_f32 v152, v88, v152, v56
	v_mul_f32_e32 v153, v153, v11
	v_mul_f32_e32 v153, v25, v153
	v_fma_f32 v153, v89, v153, v57
	v_mul_f32_e32 v154, v154, v11
	v_mul_f32_e32 v154, v26, v154
	v_fma_f32 v154, v90, v154, v58
	v_mul_f32_e32 v155, v155, v11
	v_mul_f32_e32 v155, v27, v155
	v_fma_f32 v155, v91, v155, v59
	v_cvt_pk_bf16_f32 v180, v148, v149
	v_cvt_pk_bf16_f32 v181, v150, v151
	v_cvt_pk_bf16_f32 v182, v152, v153
	v_cvt_pk_bf16_f32 v183, v154, v155
	global_store_dwordx4 v2, v[180:183], s[56:57] offset:0 sc1
	v_mul_f32_e32 v156, v156, v11
	v_mul_f32_e32 v156, v28, v156
	v_fma_f32 v156, v92, v156, v60
	v_mul_f32_e32 v157, v157, v11
	v_mul_f32_e32 v157, v29, v157
	v_fma_f32 v157, v93, v157, v61
	v_mul_f32_e32 v158, v158, v11
	v_mul_f32_e32 v158, v30, v158
	v_fma_f32 v158, v94, v158, v62
	v_mul_f32_e32 v159, v159, v11
	v_mul_f32_e32 v159, v31, v159
	v_fma_f32 v159, v95, v159, v63
	v_mul_f32_e32 v160, v160, v11
	v_mul_f32_e32 v160, v32, v160
	v_fma_f32 v160, v96, v160, v64
	v_mul_f32_e32 v161, v161, v11
	v_mul_f32_e32 v161, v33, v161
	v_fma_f32 v161, v97, v161, v65
	v_mul_f32_e32 v162, v162, v11
	v_mul_f32_e32 v162, v34, v162
	v_fma_f32 v162, v98, v162, v66
	v_mul_f32_e32 v163, v163, v11
	v_mul_f32_e32 v163, v35, v163
	v_fma_f32 v163, v99, v163, v67
	v_cvt_pk_bf16_f32 v184, v156, v157
	v_cvt_pk_bf16_f32 v185, v158, v159
	v_cvt_pk_bf16_f32 v186, v160, v161
	v_cvt_pk_bf16_f32 v187, v162, v163
	global_store_dwordx4 v2, v[184:187], s[56:57] offset:1024 sc1
	v_mul_f32_e32 v164, v164, v11
	v_mul_f32_e32 v164, v36, v164
	v_fma_f32 v164, v100, v164, v68
	v_mul_f32_e32 v165, v165, v11
	v_mul_f32_e32 v165, v37, v165
	v_fma_f32 v165, v101, v165, v69
	v_mul_f32_e32 v166, v166, v11
	v_mul_f32_e32 v166, v38, v166
	v_fma_f32 v166, v102, v166, v70
	v_mul_f32_e32 v167, v167, v11
	v_mul_f32_e32 v167, v39, v167
	v_fma_f32 v167, v103, v167, v71
	v_mul_f32_e32 v168, v168, v11
	v_mul_f32_e32 v168, v40, v168
	v_fma_f32 v168, v104, v168, v72
	v_mul_f32_e32 v169, v169, v11
	v_mul_f32_e32 v169, v41, v169
	v_fma_f32 v169, v105, v169, v73
	v_mul_f32_e32 v170, v170, v11
	v_mul_f32_e32 v170, v42, v170
	v_fma_f32 v170, v106, v170, v74
	v_mul_f32_e32 v171, v171, v11
	v_mul_f32_e32 v171, v43, v171
	v_fma_f32 v171, v107, v171, v75
	v_cvt_pk_bf16_f32 v188, v164, v165
	v_cvt_pk_bf16_f32 v189, v166, v167
	v_cvt_pk_bf16_f32 v190, v168, v169
	v_cvt_pk_bf16_f32 v191, v170, v171
	global_store_dwordx4 v2, v[188:191], s[56:57] offset:2048 sc1
	v_mul_f32_e32 v172, v172, v11
	v_mul_f32_e32 v172, v44, v172
	v_fma_f32 v172, v108, v172, v76
	v_mul_f32_e32 v173, v173, v11
	v_mul_f32_e32 v173, v45, v173
	v_fma_f32 v173, v109, v173, v77
	v_mul_f32_e32 v174, v174, v11
	v_mul_f32_e32 v174, v46, v174
	v_fma_f32 v174, v110, v174, v78
	v_mul_f32_e32 v175, v175, v11
	v_mul_f32_e32 v175, v47, v175
	v_fma_f32 v175, v111, v175, v79
	v_mul_f32_e32 v176, v176, v11
	v_mul_f32_e32 v176, v48, v176
	v_fma_f32 v176, v112, v176, v80
	v_mul_f32_e32 v177, v177, v11
	v_mul_f32_e32 v177, v49, v177
	v_fma_f32 v177, v113, v177, v81
	v_mul_f32_e32 v178, v178, v11
	v_mul_f32_e32 v178, v50, v178
	v_fma_f32 v178, v114, v178, v82
	v_mul_f32_e32 v179, v179, v11
	v_mul_f32_e32 v179, v51, v179
	v_fma_f32 v179, v115, v179, v83
	v_cvt_pk_bf16_f32 v192, v172, v173
	v_cvt_pk_bf16_f32 v193, v174, v175
	v_cvt_pk_bf16_f32 v194, v176, v177
	v_cvt_pk_bf16_f32 v195, v178, v179
	global_store_dwordx4 v2, v[192:195], s[56:57] offset:3072 sc1
	s_branch .Lnr6_done

.Lnr6_orig:
	s_lshl_b32 s0, s96, 3
	s_add_i32 s2, s93, s0
	s_cmpk_gt_i32 s2, 0x23ff
	s_cbranch_scc1 .LBB0_759
	s_waitcnt vmcnt(0)
	v_mbcnt_hi_u32_b32 v1, -1, v212
	v_and_b32_e32 v4, 0xffffffc0, v1
	v_add_u32_e32 v4, 64, v4
	v_xor_b32_e32 v5, 1, v1
	v_cmp_lt_i32_e32 vcc, v5, v4
	v_readlane_b32 s36, v244, 3
	v_lshlrev_b32_e32 v0, 2, v1
	v_cndmask_b32_e32 v5, v1, v5, vcc
	v_lshlrev_b32_e32 v32, 2, v5
	v_xor_b32_e32 v5, 2, v1
	v_cmp_lt_i32_e32 vcc, v5, v4
	v_readlane_b32 s48, v244, 15
	v_readlane_b32 s49, v244, 16
	v_cndmask_b32_e32 v5, v1, v5, vcc
	v_lshlrev_b32_e32 v33, 2, v5
	v_xor_b32_e32 v5, 4, v1
	v_cmp_lt_i32_e32 vcc, v5, v4
	v_and_b32_e32 v0, 0xfc, v0
	v_readlane_b32 s50, v244, 17
	v_cndmask_b32_e32 v5, v1, v5, vcc
	v_lshlrev_b32_e32 v34, 2, v5
	v_xor_b32_e32 v5, 8, v1
	v_cmp_lt_i32_e32 vcc, v5, v4
	v_readlane_b32 s51, v244, 18
	s_mov_b64 s[12:13], s[48:49]
	v_cndmask_b32_e32 v5, v1, v5, vcc
	v_lshlrev_b32_e32 v35, 2, v5
	v_xor_b32_e32 v5, 16, v1
	v_cmp_lt_i32_e32 vcc, v5, v4
	v_mov_b32_e32 v3, 0
	v_lshlrev_b32_e32 v2, 2, v0
	v_cndmask_b32_e32 v5, v1, v5, vcc
	v_lshlrev_b32_e32 v36, 2, v5
	v_xor_b32_e32 v5, 32, v1
	s_mov_b64 s[14:15], s[50:51]
	v_or_b32_e32 v14, 0x400, v0
	v_lshl_add_u64 v[16:17], s[8:9], 0, v[2:3]
	v_cmp_lt_i32_e32 vcc, v5, v4
	v_lshl_add_u64 v[20:21], s[14:15], 0, v[2:3]
	v_lshlrev_b32_e32 v2, 2, v14
	v_or_b32_e32 v30, 0x500, v0
	v_cndmask_b32_e32 v4, v1, v5, vcc
	v_and_b32_e32 v7, 1, v1
	v_lshlrev_b32_e32 v1, 3, v1
	v_lshl_add_u64 v[22:23], s[14:15], 0, v[2:3]
	v_lshlrev_b32_e32 v2, 2, v30
	v_or_b32_e32 v48, 0x700, v0
	v_lshlrev_b32_e32 v37, 2, v4
	v_and_b32_e32 v4, 0x1f0, v1
	v_mov_b32_e32 v5, v3
	v_or_b32_e32 v6, 0x600, v0
	v_lshl_add_u64 v[24:25], s[14:15], 0, v[2:3]
	v_lshlrev_b32_e32 v2, 2, v48
	s_lshl_b32 s18, s87, 3
	v_lshl_add_u64 v[4:5], s[76:77], 0, v[4:5]
	v_lshlrev_b32_e32 v8, 2, v6
	v_mov_b32_e32 v9, v3
	v_lshl_add_u64 v[26:27], s[14:15], 0, v[2:3]
	v_lshlrev_b32_e32 v2, 9, v7
	s_add_u32 s19, s76, 0x14000
	v_lshl_add_u64 v[18:19], s[14:15], 0, v[8:9]
	v_or_b32_e32 v8, 0x100, v0
	v_or_b32_e32 v10, 0x200, v0
	v_or_b32_e32 v12, 0x300, v0
	v_lshl_add_u64 v[2:3], v[4:5], 0, v[2:3]
	s_mov_b64 s[4:5], 0x11189000
	s_addc_u32 s20, s77, 0
	v_cmp_eq_u32_e64 s[0:1], 0, v7
	v_lshl_add_u64 v[28:29], v[2:3], 0, s[4:5]
	s_movk_i32 s21, 0x1000
	v_mov_b32_e32 v38, 0x358637bd
	s_mov_b32 s22, 0xf800000
	v_mov_b32_e32 v39, 0x260
	v_lshlrev_b32_e32 v40, 2, v0
	v_lshlrev_b32_e32 v41, 2, v8
	v_lshlrev_b32_e32 v42, 2, v10
	v_lshlrev_b32_e32 v43, 2, v12
	s_mov_b64 s[6:7], 0x400
	v_lshlrev_b32_e32 v44, 2, v14
	v_lshlrev_b32_e32 v45, 2, v30
	s_mov_b64 s[10:11], 0x800
	v_lshlrev_b32_e32 v46, 2, v6
	v_lshlrev_b32_e32 v47, 2, v48
	s_mov_b64 s[12:13], 0xc00
	v_readlane_b32 s37, v244, 4
	v_readlane_b32 s38, v244, 5
	v_readlane_b32 s39, v244, 6
	v_readlane_b32 s40, v244, 7
	v_readlane_b32 s41, v244, 8
	v_readlane_b32 s42, v244, 9
	v_readlane_b32 s43, v244, 10
	v_readlane_b32 s44, v244, 11
	v_readlane_b32 s45, v244, 12
	v_readlane_b32 s46, v244, 13
	v_readlane_b32 s47, v244, 14

.LBB0_1020:
	s_cmp_lt_i32 s78, 10
	s_cselect_b64 s[0:1], -1, 0
	s_cmp_gt_i32 s79, 9
	s_cselect_b64 s[2:3], -1, 0
	s_and_b64 s[0:1], s[0:1], s[2:3]
	s_andn2_b64 vcc, exec, s[0:1]
	s_cbranch_vccnz .LBB0_1081
	s_cmp_lg_u32 s87, 0x100
	s_cbranch_scc1 .Lnr9_orig
	v_mbcnt_hi_u32_b32 v0, -1, v212
	v_and_b32_e32 v0, 63, v0
	v_lshlrev_b32_e32 v1, 5, v0
	v_lshlrev_b32_e32 v2, 4, v0
	v_mov_b32_e32 v9, 0x358637bd
	v_mov_b32_e32 v10, 0x260
	v_xor_b32_e32 v3, 1, v0
	v_lshlrev_b32_e32 v3, 2, v3
	v_xor_b32_e32 v4, 2, v0
	v_lshlrev_b32_e32 v4, 2, v4
	v_xor_b32_e32 v5, 4, v0
	v_lshlrev_b32_e32 v5, 2, v5
	v_xor_b32_e32 v6, 8, v0
	v_lshlrev_b32_e32 v6, 2, v6
	v_xor_b32_e32 v7, 16, v0
	v_lshlrev_b32_e32 v7, 2, v7
	v_xor_b32_e32 v8, 32, v0
	v_lshlrev_b32_e32 v8, 2, v8
	s_lshl_b32 s31, s96, 3
	s_add_u32 s31, s31, s93
	s_add_u32 s58, s76, 0xc989000
	s_addc_u32 s59, s77, 0
	s_add_u32 s62, s76, 0x11189000
	s_addc_u32 s63, s77, 0
	s_add_u32 s64, s76, 0x4a000
	s_addc_u32 s65, s77, 0
	v_readlane_b32 s50, v244, 15
	v_readlane_b32 s51, v244, 16
	s_mov_b32 s23, -1
	s_mul_i32 s5, s31, 9
	s_lshr_b32 s5, s5, 1
	s_add_u32 s16, s31, 1
	s_mul_i32 s16, s16, 9
	s_lshr_b32 s16, s16, 1
	s_nop 0
	s_add_u32 s50, s50, 0x2000
	s_addc_u32 s51, s51, 0
	s_add_u32 s54, s50, 0x1000
	s_addc_u32 s55, s51, 0
	s_cmp_ge_u32 s5, s16
	s_cbranch_scc1 .Lnr9_done
	global_load_dwordx4 v[20:23], v1, s[50:51] offset:0
	global_load_dwordx4 v[24:27], v1, s[50:51] offset:16
	global_load_dwordx4 v[28:31], v1, s[50:51] offset:2048
	global_load_dwordx4 v[32:35], v1, s[50:51] offset:2064
	global_load_dwordx4 v[36:39], v1, s[54:55] offset:0
	global_load_dwordx4 v[40:43], v1, s[54:55] offset:16
	global_load_dwordx4 v[44:47], v1, s[54:55] offset:2048
	global_load_dwordx4 v[48:51], v1, s[54:55] offset:2064
	s_lshl_b32 s35, s5, 13
	s_add_u32 s2, s58, s35
	s_addc_u32 s3, s59, 0
	s_add_u32 s6, s2, 0x1000
	s_addc_u32 s7, s3, 0
	global_load_dwordx4 v[116:119], v1, s[2:3] offset:0
	global_load_dwordx4 v[120:123], v1, s[2:3] offset:16
	global_load_dwordx4 v[124:127], v1, s[2:3] offset:2048
	global_load_dwordx4 v[128:131], v1, s[2:3] offset:2064
	global_load_dwordx4 v[132:135], v1, s[6:7] offset:0
	global_load_dwordx4 v[136:139], v1, s[6:7] offset:16
	global_load_dwordx4 v[140:143], v1, s[6:7] offset:2048
	global_load_dwordx4 v[144:147], v1, s[6:7] offset:2064
	s_waitcnt vmcnt(8)

.Lnr9_orig:
	s_lshl_b32 s0, s96, 3
	s_add_i32 s2, s93, s0
	s_cmpk_gt_i32 s2, 0x23ff
	s_cbranch_scc1 .LBB0_1024
	s_waitcnt vmcnt(0)
	v_mbcnt_hi_u32_b32 v1, -1, v212
	v_and_b32_e32 v4, 0xffffffc0, v1
	v_add_u32_e32 v4, 64, v4
	v_xor_b32_e32 v5, 1, v1
	v_cmp_lt_i32_e32 vcc, v5, v4
	v_readlane_b32 s36, v244, 3
	v_readlane_b32 s48, v244, 15
	v_cndmask_b32_e32 v5, v1, v5, vcc
	v_lshlrev_b32_e32 v38, 2, v5
	v_xor_b32_e32 v5, 2, v1
	v_cmp_lt_i32_e32 vcc, v5, v4
	v_readlane_b32 s49, v244, 16
	v_lshlrev_b32_e32 v0, 2, v1
	v_cndmask_b32_e32 v5, v1, v5, vcc
	v_lshlrev_b32_e32 v39, 2, v5
	v_xor_b32_e32 v5, 4, v1
	v_cmp_lt_i32_e32 vcc, v5, v4
	s_lshl_b32 s18, s87, 3
	v_readlane_b32 s50, v244, 17
	v_cndmask_b32_e32 v5, v1, v5, vcc
	v_readlane_b32 s51, v244, 18
	s_mov_b64 s[12:13], s[48:49]
	v_and_b32_e32 v0, 0xfc, v0
	v_lshlrev_b32_e32 v40, 2, v5
	v_xor_b32_e32 v5, 8, v1
	s_add_u32 s4, s12, 0x2000
	v_mov_b32_e32 v3, 0
	v_cmp_lt_i32_e32 vcc, v5, v4
	v_or_b32_e32 v6, 0x600, v0
	s_addc_u32 s5, s13, 0
	v_cndmask_b32_e32 v5, v1, v5, vcc
	v_lshlrev_b32_e32 v8, 2, v6
	v_mov_b32_e32 v9, v3
	v_lshlrev_b32_e32 v2, 2, v0
	v_lshlrev_b32_e32 v41, 2, v5
	v_xor_b32_e32 v5, 16, v1
	v_lshl_add_u64 v[18:19], s[4:5], 0, v[8:9]
	v_or_b32_e32 v8, 0x100, v0
	v_lshl_add_u64 v[16:17], s[8:9], 0, v[2:3]
	v_cmp_lt_i32_e32 vcc, v5, v4
	v_lshl_add_u64 v[20:21], s[4:5], 0, v[2:3]
	v_lshlrev_b32_e32 v2, 2, v8
	v_or_b32_e32 v10, 0x200, v0
	v_cndmask_b32_e32 v5, v1, v5, vcc
	v_lshl_add_u64 v[22:23], s[4:5], 0, v[2:3]
	v_lshlrev_b32_e32 v2, 2, v10
	v_or_b32_e32 v12, 0x300, v0
	v_lshlrev_b32_e32 v42, 2, v5
	v_xor_b32_e32 v5, 32, v1
	v_lshl_add_u64 v[24:25], s[4:5], 0, v[2:3]
	v_lshlrev_b32_e32 v2, 2, v12
	v_or_b32_e32 v14, 0x400, v0
	v_cmp_lt_i32_e32 vcc, v5, v4
	v_lshl_add_u64 v[26:27], s[4:5], 0, v[2:3]
	v_lshlrev_b32_e32 v2, 2, v14
	v_or_b32_e32 v36, 0x500, v0
	v_cndmask_b32_e32 v4, v1, v5, vcc
	v_and_b32_e32 v7, 1, v1
	v_lshlrev_b32_e32 v1, 3, v1
	v_lshl_add_u64 v[28:29], s[4:5], 0, v[2:3]
	v_lshlrev_b32_e32 v2, 2, v36
	v_or_b32_e32 v54, 0x700, v0
	v_lshlrev_b32_e32 v43, 2, v4
	v_and_b32_e32 v4, 0x1f0, v1
	v_mov_b32_e32 v5, v3
	v_lshl_add_u64 v[30:31], s[4:5], 0, v[2:3]
	v_lshlrev_b32_e32 v2, 2, v54
	v_lshl_add_u64 v[4:5], s[76:77], 0, v[4:5]
	v_lshl_add_u64 v[32:33], s[4:5], 0, v[2:3]
	v_lshlrev_b32_e32 v2, 9, v7
	s_add_u32 s19, s76, 0x4a000
	v_lshl_add_u64 v[2:3], v[4:5], 0, v[2:3]
	s_mov_b64 s[4:5], 0x11189000
	s_addc_u32 s20, s77, 0
	v_cmp_eq_u32_e64 s[0:1], 0, v7
	v_lshl_add_u64 v[34:35], v[2:3], 0, s[4:5]
	s_movk_i32 s21, 0x1000
	v_mov_b32_e32 v44, 0x358637bd
	s_mov_b32 s22, 0xf800000
	v_mov_b32_e32 v45, 0x260
	v_lshlrev_b32_e32 v46, 2, v0
	v_lshlrev_b32_e32 v47, 2, v8
	v_lshlrev_b32_e32 v48, 2, v10
	v_lshlrev_b32_e32 v49, 2, v12
	s_mov_b64 s[6:7], 0x400
	v_lshlrev_b32_e32 v50, 2, v14
	v_lshlrev_b32_e32 v51, 2, v36
	s_mov_b64 s[10:11], 0x800
	v_lshlrev_b32_e32 v52, 2, v6
	v_lshlrev_b32_e32 v53, 2, v54
	s_mov_b64 s[12:13], 0xc00
	v_readlane_b32 s37, v244, 4
	v_readlane_b32 s38, v244, 5
	v_readlane_b32 s39, v244, 6
	v_readlane_b32 s40, v244, 7
	v_readlane_b32 s41, v244, 8
	v_readlane_b32 s42, v244, 9
	v_readlane_b32 s43, v244, 10
	v_readlane_b32 s44, v244, 11
	v_readlane_b32 s45, v244, 12
	v_readlane_b32 s46, v244, 13
	v_readlane_b32 s47, v244, 14
	s_mov_b64 s[14:15], s[50:51]

.LBB0_1397:
	s_cmp_lt_i32 s78, 14
	s_cselect_b64 s[0:1], -1, 0
	s_cmp_gt_i32 s79, 13
	s_cselect_b64 s[2:3], -1, 0
	s_and_b64 s[0:1], s[0:1], s[2:3]
	s_andn2_b64 vcc, exec, s[0:1]
	s_cbranch_vccnz .LBB0_1460
	s_cmp_lg_u32 s87, 0x100
	s_cbranch_scc1 .Lnr13_orig
	v_mbcnt_hi_u32_b32 v0, -1, v212
	v_and_b32_e32 v0, 63, v0
	v_lshlrev_b32_e32 v1, 5, v0
	v_lshlrev_b32_e32 v2, 4, v0
	v_mov_b32_e32 v9, 0x358637bd
	v_mov_b32_e32 v10, 0x260
	v_xor_b32_e32 v3, 1, v0
	v_lshlrev_b32_e32 v3, 2, v3
	v_xor_b32_e32 v4, 2, v0
	v_lshlrev_b32_e32 v4, 2, v4
	v_xor_b32_e32 v5, 4, v0
	v_lshlrev_b32_e32 v5, 2, v5
	v_xor_b32_e32 v6, 8, v0
	v_lshlrev_b32_e32 v6, 2, v6
	v_xor_b32_e32 v7, 16, v0
	v_lshlrev_b32_e32 v7, 2, v7
	v_xor_b32_e32 v8, 32, v0
	v_lshlrev_b32_e32 v8, 2, v8
	s_lshl_b32 s31, s96, 3
	s_add_u32 s31, s31, s93
	s_add_u32 s58, s76, 0xc989000
	s_addc_u32 s59, s77, 0
	s_add_u32 s62, s76, 0x11189000
	s_addc_u32 s63, s77, 0
	s_add_u32 s64, s76, 0x50000
	s_addc_u32 s65, s77, 0
	v_readlane_b32 s50, v244, 17
	v_readlane_b32 s51, v244, 18
	s_mov_b32 s23, -1
	s_lshl_b32 s35, s31, 2
	s_lshr_b32 s25, s35, 11
	s_and_b32 s35, s35, 0x7ff
	s_mul_i32 s5, s25, 0x900
	s_add_u32 s5, s5, s35
	s_add_u32 s5, s5, 0x100
	s_add_u32 s16, s5, 4
	s_nop 0
	s_add_u32 s50, s50, 0x2000
	s_addc_u32 s51, s51, 0
	s_add_u32 s54, s50, 0x1000
	s_addc_u32 s55, s51, 0
	s_cmp_ge_u32 s5, s16
	s_cbranch_scc1 .Lnr13_done
	global_load_dwordx4 v[20:23], v1, s[50:51] offset:0
	global_load_dwordx4 v[24:27], v1, s[50:51] offset:16
	global_load_dwordx4 v[28:31], v1, s[50:51] offset:2048
	global_load_dwordx4 v[32:35], v1, s[50:51] offset:2064
	global_load_dwordx4 v[36:39], v1, s[54:55] offset:0
	global_load_dwordx4 v[40:43], v1, s[54:55] offset:16
	global_load_dwordx4 v[44:47], v1, s[54:55] offset:2048
	global_load_dwordx4 v[48:51], v1, s[54:55] offset:2064
	s_lshl_b32 s35, s5, 13
	s_add_u32 s2, s58, s35
	s_addc_u32 s3, s59, 0
	s_add_u32 s6, s2, 0x1000
	s_addc_u32 s7, s3, 0
	global_load_dwordx4 v[116:119], v1, s[2:3] offset:0
	global_load_dwordx4 v[120:123], v1, s[2:3] offset:16
	global_load_dwordx4 v[124:127], v1, s[2:3] offset:2048
	global_load_dwordx4 v[128:131], v1, s[2:3] offset:2064
	global_load_dwordx4 v[132:135], v1, s[6:7] offset:0
	global_load_dwordx4 v[136:139], v1, s[6:7] offset:16
	global_load_dwordx4 v[140:143], v1, s[6:7] offset:2048
	global_load_dwordx4 v[144:147], v1, s[6:7] offset:2064
	s_waitcnt vmcnt(8)

.Lnr13_orig:
	s_lshl_b32 s0, s96, 3
	s_add_i32 s2, s93, s0
	s_cmpk_gt_i32 s2, 0x23ff
	s_cbranch_scc1 .LBB0_1403
	s_waitcnt vmcnt(0)
	v_mbcnt_hi_u32_b32 v1, -1, v212
	v_and_b32_e32 v4, 0xffffffc0, v1
	v_add_u32_e32 v4, 64, v4
	v_xor_b32_e32 v5, 1, v1
	v_cmp_lt_i32_e32 vcc, v5, v4
	v_readlane_b32 s36, v244, 3
	v_readlane_b32 s50, v244, 17
	v_cndmask_b32_e32 v5, v1, v5, vcc
	v_lshlrev_b32_e32 v52, 2, v5
	v_xor_b32_e32 v5, 2, v1
	v_cmp_lt_i32_e32 vcc, v5, v4
	v_readlane_b32 s51, v244, 18
	s_lshl_b32 s18, s87, 3
	v_cndmask_b32_e32 v5, v1, v5, vcc
	v_lshlrev_b32_e32 v53, 2, v5
	v_xor_b32_e32 v5, 4, v1
	v_cmp_lt_i32_e32 vcc, v5, v4
	s_mov_b64 s[14:15], s[50:51]
	v_lshlrev_b32_e32 v0, 2, v1
	v_cndmask_b32_e32 v5, v1, v5, vcc
	v_lshlrev_b32_e32 v54, 2, v5
	v_xor_b32_e32 v5, 8, v1
	s_add_u32 s4, s14, 0x2000
	v_and_b32_e32 v0, 0xfc, v0
	v_cmp_lt_i32_e32 vcc, v5, v4
	s_addc_u32 s5, s15, 0
	v_mov_b32_e32 v3, 0
	v_lshlrev_b32_e32 v2, 2, v0
	v_cndmask_b32_e32 v5, v1, v5, vcc
	v_or_b32_e32 v6, 0x100, v0
	v_lshl_add_u64 v[32:33], s[8:9], 0, v[2:3]
	v_lshlrev_b32_e32 v55, 2, v5
	v_xor_b32_e32 v5, 16, v1
	v_lshl_add_u64 v[34:35], s[4:5], 0, v[2:3]
	v_lshlrev_b32_e32 v2, 2, v6
	v_or_b32_e32 v8, 0x200, v0
	v_cmp_lt_i32_e32 vcc, v5, v4
	v_lshl_add_u64 v[36:37], s[4:5], 0, v[2:3]
	v_lshlrev_b32_e32 v2, 2, v8
	v_or_b32_e32 v10, 0x300, v0
	v_cndmask_b32_e32 v5, v1, v5, vcc
	v_lshl_add_u64 v[38:39], s[4:5], 0, v[2:3]
	v_lshlrev_b32_e32 v2, 2, v10
	v_or_b32_e32 v12, 0x400, v0
	v_lshlrev_b32_e32 v56, 2, v5
	v_xor_b32_e32 v5, 32, v1
	v_lshl_add_u64 v[40:41], s[4:5], 0, v[2:3]
	v_lshlrev_b32_e32 v2, 2, v12
	v_or_b32_e32 v14, 0x500, v0
	v_cmp_lt_i32_e32 vcc, v5, v4
	v_lshl_add_u64 v[42:43], s[4:5], 0, v[2:3]
	v_lshlrev_b32_e32 v2, 2, v14
	v_or_b32_e32 v16, 0x600, v0
	v_cndmask_b32_e32 v4, v1, v5, vcc
	v_and_b32_e32 v7, 1, v1
	v_lshlrev_b32_e32 v1, 3, v1
	v_lshl_add_u64 v[44:45], s[4:5], 0, v[2:3]
	v_lshlrev_b32_e32 v2, 2, v16
	v_or_b32_e32 v18, 0x700, v0
	v_lshlrev_b32_e32 v57, 2, v4
	v_and_b32_e32 v4, 0x1f0, v1
	v_mov_b32_e32 v5, v3
	v_lshl_add_u64 v[46:47], s[4:5], 0, v[2:3]
	v_lshlrev_b32_e32 v2, 2, v18
	v_lshl_add_u64 v[4:5], s[76:77], 0, v[4:5]
	v_lshl_add_u64 v[48:49], s[4:5], 0, v[2:3]
	v_lshlrev_b32_e32 v2, 9, v7
	v_lshl_add_u64 v[2:3], v[4:5], 0, v[2:3]
	s_mov_b64 s[4:5], 0x11189000
	v_cmp_eq_u32_e64 s[0:1], 0, v7
	v_lshl_add_u64 v[50:51], v[2:3], 0, s[4:5]
	s_movk_i32 s19, 0x1000
	v_mov_b32_e32 v58, 0x358637bd
	s_mov_b32 s20, 0xf800000
	v_mov_b32_e32 v59, 0x260
	v_lshlrev_b32_e32 v60, 2, v0
	v_lshlrev_b32_e32 v61, 2, v6
	v_lshlrev_b32_e32 v62, 2, v8
	v_lshlrev_b32_e32 v63, 2, v10
	s_mov_b64 s[6:7], 0x400
	v_lshlrev_b32_e32 v64, 2, v12
	v_lshlrev_b32_e32 v65, 2, v14
	s_mov_b64 s[10:11], 0x800
	v_lshlrev_b32_e32 v66, 2, v16
	v_lshlrev_b32_e32 v67, 2, v18
	s_mov_b64 s[12:13], 0xc00
	v_readlane_b32 s37, v244, 4
	v_readlane_b32 s38, v244, 5
	v_readlane_b32 s39, v244, 6
	v_readlane_b32 s40, v244, 7
	v_readlane_b32 s41, v244, 8
	v_readlane_b32 s42, v244, 9
	v_readlane_b32 s43, v244, 10
	v_readlane_b32 s44, v244, 11
	v_readlane_b32 s45, v244, 12
	v_readlane_b32 s46, v244, 13
	v_readlane_b32 s47, v244, 14
	v_readlane_b32 s48, v244, 15
	v_readlane_b32 s49, v244, 16
	s_branch .LBB0_1401
